# one idle workgroup per XCD pre-flushes its L2 (buffer_wbl2) at the start of its ~25 us wait at the GEMM1->mixer grid barrier; on top of stage B
# baseline (speedup 1.0000x reference)
; #define PG8_WAIT_V(n) asm volatile("s_waitcnt vmcnt(" #n ")" ::: "memory")
; #define PG8_BAR __builtin_amdgcn_s_barrier()
; template <class Epi, class Sched, bool ALIGN_EPI = false, bool SP2 = true>
; DI void gemm_phase(LAS unsigned char* lds, const Gemm g, const Sched& S, const Epi& E, f32x4 (&acc)[2][2][4][2]) {
;     ...
;     PG8_WAIT_V(0);
;     if constexpr (!ALIGN_EPI) { if (wr == 0) PG8_BAR; }
;     PG8_BAR;
; template <int PH> __global__ void __launch_bounds__(512, 2) fwd(Params p) {
;     ...
;     if (PH < 0) xcd_barrier(xb);
.LBB0_341:
	s_cmp_lg_u32 s78, 3
	s_cbranch_scc1 .Lpf_done
	s_lshr_b32 s100, s2, 3
	s_cmp_lg_u32 s100, 31
	s_cbranch_scc1 .Lpf_done
	v_readfirstlane_b32 s100, v179
	s_cmp_gt_u32 s100, 63
	s_cbranch_scc1 .Lpf_done
	s_waitcnt vmcnt(0)
	buffer_wbl2 sc1
